# v8 with every s_setprio removed from the 5 GEMM unit loops (no static raise), baseline placement
# baseline (speedup 1.0000x reference)
; #define PG8_STAGE(bufoff, gbase, voff) do { _Pragma("unroll") for (int _i = 0; _i < 2; ++_i) \
;         __builtin_amdgcn_global_load_lds((const unsigned*)((const char*)(gbase) + (voff)[_i]), (LAS unsigned*)(lds + (bufoff) + ldsw + _i * 8192), 16, 0, 0); } while (0)
; #define PG8_WAIT_V(n) asm volatile("s_waitcnt vmcnt(" #n ")" ::: "memory")
; #define PG8_BAR __builtin_amdgcn_s_barrier()
; template <class Epi, class Sched>
; __device__ __forceinline__ void gemm_phase(LAS unsigned char* lds, const Gemm g, const Sched& S, const Epi& E) {
;     ...
;     f32x4 acc[2][2][4][2];
; #pragma unroll
;     for (int a = 0; a < 2; ++a)
; #pragma unroll
;         for (int b = 0; b < 2; ++b)
; #pragma unroll
;             for (int m = 0; m < 4; ++m)
; #pragma unroll
;                 for (int n = 0; n < 2; ++n) acc[a][b][m][n] = (f32x4){0.f, 0.f, 0.f, 0.f};
;     ...
;     PG8_STAGE(PG8_SB(0, 0), cB, voffB); PG8_STAGE(PG8_SB(0, 1), cB + hstepB, voffB); PG8_STAGE(PG8_SA(0, 0), cA, voffA); PG8_STAGE(PG8_SA(0, 1), cA + hstepA, voffA);
;     if (wr == 1) PG8_BAR;
;     PG8_WAIT_V(2); PG8_BAR;
;     PG8_STAGE(PG8_SB(1, 0), cB + kstep, voffB); PG8_STAGE(PG8_SA(1, 0), cA + kstep, voffA); PG8_STAGE(PG8_SB(1, 1), cB + hstepB + kstep, voffB);
;     PG8_WAIT_V(6); PG8_BAR;
;     for (;;) {
.LBB0_267:
	v_lshl_add_u64 v[14:15], s[24:25], 0, v[4:5]
	v_mov_b32_e32 v3, v5
	v_and_b32_e32 v142, 15, v143
	v_and_b32_e32 v22, 48, v143
	v_lshlrev_b32_e32 v23, 2, v143
	v_lshl_add_u64 v[16:17], s[24:25], 0, v[2:3]
	s_and_b32 s48, s44, 3
	v_lshl_or_b32 v22, v142, 6, v22
	s_lshl_b32 s4, s47, 13
	v_and_b32_e32 v23, 32, v23
	s_add_i32 m0, s50, 0x18000
	v_lshl_add_u64 v[14:15], v[14:15], 0, s[36:37]
	v_lshl_add_u64 v[18:19], s[20:21], 0, v[4:5]
	v_bitop3_b32 v24, v22, s4, v23 bitop3:0xde
	s_lshl_b32 s4, s48, 12
	s_waitcnt vmcnt(2)
	s_barrier
	global_load_lds_dwordx4 v[14:15], off
	v_lshl_add_u64 v[14:15], v[16:17], 0, s[36:37]
	s_add_i32 m0, s50, 0x1a000
	s_add_i32 s54, s50, 0x8000
	s_add_i32 s55, s50, 0xa000
	v_lshl_add_u64 v[20:21], s[20:21], 0, v[2:3]
	v_bitop3_b32 v144, v22, s4, v23 bitop3:0xde
	global_load_lds_dwordx4 v[14:15], off
	v_lshl_add_u64 v[14:15], v[18:19], 0, s[36:37]
	s_mov_b32 m0, s54
	s_add_u32 s4, s24, 0x158080
	global_load_lds_dwordx4 v[14:15], off
	v_lshl_add_u64 v[14:15], v[20:21], 0, s[36:37]
	s_mov_b32 m0, s55
	s_addc_u32 s5, s25, 0
	global_load_lds_dwordx4 v[14:15], off
	s_add_i32 m0, s50, 0x1c000
	v_lshl_add_u64 v[14:15], s[4:5], 0, v[4:5]
	global_load_lds_dwordx4 v[14:15], off
	v_lshl_add_u64 v[14:15], s[4:5], 0, v[2:3]
	s_add_i32 m0, s50, 0x1e000
	s_movk_i32 s10, 0x1580
	global_load_lds_dwordx4 v[14:15], off
	v_lshrrev_b32_e32 v11, 1, v11
	v_mul_lo_u32 v10, v10, s10
	s_mov_b32 s22, 0x15800
	v_mad_u64_u32 v[10:11], s[4:5], v11, s22, v[10:11]
	v_or_b32_e32 v10, v10, v12
	v_add_lshl_u32 v134, v10, v13, 1
	v_lshrrev_b32_e32 v10, 1, v6
	v_mul_lo_u32 v6, v7, s10
	v_mad_u64_u32 v[6:7], s[4:5], v10, s22, v[6:7]
	s_waitcnt vmcnt(6)
	v_or_b32_e32 v6, v6, v8
	s_cmpk_lt_u32 s45, 0x100
	v_add_lshl_u32 v136, v6, v9, 1
	v_mov_b32_e32 v6, 0
	v_readlane_b32 s4, v254, 13
	s_cselect_b64 s[18:19], -1, 0
	v_mov_b32_e32 v135, v5
	v_mov_b32_e32 v137, v5
	s_mov_b32 s59, 0
	v_add_u32_e32 v145, 0, v24
	s_mov_b32 s10, s4
	v_readlane_b32 s46, v253, 61
	v_mov_b32_e32 v7, v6
	v_mov_b32_e32 v8, v6
	v_mov_b32_e32 v9, v6
	v_mov_b32_e32 v10, v6
	v_mov_b32_e32 v11, v6
	v_mov_b32_e32 v12, v6
	v_mov_b32_e32 v13, v6
	v_mov_b32_e32 v14, v6
	v_mov_b32_e32 v15, v6
	v_mov_b32_e32 v16, v6
	v_mov_b32_e32 v17, v6
	v_mov_b32_e32 v18, v6
	v_mov_b32_e32 v19, v6
	v_mov_b32_e32 v20, v6
	v_mov_b32_e32 v21, v6
	v_mov_b32_e32 v22, v6
	v_mov_b32_e32 v23, v6
	v_mov_b32_e32 v24, v6
	v_mov_b32_e32 v25, v6
	v_mov_b32_e32 v30, v6
	v_mov_b32_e32 v31, v6
	v_mov_b32_e32 v32, v6
	v_mov_b32_e32 v33, v6
	v_mov_b32_e32 v38, v6
	v_mov_b32_e32 v39, v6
	v_mov_b32_e32 v40, v6
	v_mov_b32_e32 v41, v6
	v_mov_b32_e32 v46, v6
	v_mov_b32_e32 v47, v6
	v_mov_b32_e32 v48, v6
	v_mov_b32_e32 v49, v6
	v_mov_b32_e32 v26, v6
	v_mov_b32_e32 v27, v6
	v_mov_b32_e32 v28, v6
	v_mov_b32_e32 v29, v6
	v_mov_b32_e32 v34, v6
	v_mov_b32_e32 v35, v6
	v_mov_b32_e32 v36, v6
	v_mov_b32_e32 v37, v6
	v_mov_b32_e32 v42, v6
	v_mov_b32_e32 v43, v6
	v_mov_b32_e32 v44, v6
	v_mov_b32_e32 v45, v6
	v_mov_b32_e32 v50, v6
	v_mov_b32_e32 v51, v6
	v_mov_b32_e32 v52, v6
	v_mov_b32_e32 v53, v6
	v_mov_b32_e32 v54, v6
	v_mov_b32_e32 v55, v6
	v_mov_b32_e32 v56, v6
	v_mov_b32_e32 v57, v6
	v_mov_b32_e32 v58, v6
	v_mov_b32_e32 v59, v6
	v_mov_b32_e32 v60, v6
	v_mov_b32_e32 v61, v6
	v_mov_b32_e32 v62, v6
	v_mov_b32_e32 v63, v6
	v_mov_b32_e32 v64, v6
	v_mov_b32_e32 v65, v6
	v_mov_b32_e32 v66, v6
	v_mov_b32_e32 v67, v6
	v_mov_b32_e32 v68, v6
	v_mov_b32_e32 v69, v6
	v_mov_b32_e32 v70, v6
	v_mov_b32_e32 v71, v6
	v_mov_b32_e32 v72, v6
	v_mov_b32_e32 v73, v6
	v_mov_b32_e32 v74, v6
	v_mov_b32_e32 v75, v6
	v_mov_b32_e32 v76, v6
	v_mov_b32_e32 v77, v6
	v_mov_b32_e32 v78, v6
	v_mov_b32_e32 v79, v6
	v_mov_b32_e32 v80, v6
	v_mov_b32_e32 v81, v6
	v_mov_b32_e32 v82, v6
	v_mov_b32_e32 v83, v6
	v_mov_b32_e32 v84, v6
	v_mov_b32_e32 v85, v6
	v_mov_b32_e32 v86, v6
	v_mov_b32_e32 v87, v6
	v_mov_b32_e32 v88, v6
	v_mov_b32_e32 v89, v6
	v_mov_b32_e32 v94, v6
	v_mov_b32_e32 v95, v6
	v_mov_b32_e32 v96, v6
	v_mov_b32_e32 v97, v6
	v_mov_b32_e32 v102, v6
	v_mov_b32_e32 v103, v6
	v_mov_b32_e32 v104, v6
	v_mov_b32_e32 v105, v6
	v_mov_b32_e32 v114, v6
	v_mov_b32_e32 v115, v6
	v_mov_b32_e32 v116, v6
	v_mov_b32_e32 v117, v6
	v_mov_b32_e32 v90, v6
	v_mov_b32_e32 v91, v6
	v_mov_b32_e32 v92, v6
	v_mov_b32_e32 v93, v6
	v_mov_b32_e32 v98, v6
	v_mov_b32_e32 v99, v6
	v_mov_b32_e32 v100, v6
	v_mov_b32_e32 v101, v6
	v_mov_b32_e32 v106, v6
	v_mov_b32_e32 v107, v6
	v_mov_b32_e32 v108, v6
	v_mov_b32_e32 v109, v6
	v_mov_b32_e32 v110, v6
	v_mov_b32_e32 v111, v6
	v_mov_b32_e32 v112, v6
	v_mov_b32_e32 v113, v6
	v_mov_b32_e32 v118, v6
	v_mov_b32_e32 v119, v6
	v_mov_b32_e32 v120, v6
	v_mov_b32_e32 v121, v6
	v_mov_b32_e32 v122, v6
	v_mov_b32_e32 v123, v6
	v_mov_b32_e32 v124, v6
	v_mov_b32_e32 v125, v6
	v_mov_b32_e32 v126, v6
	v_mov_b32_e32 v127, v6
	v_mov_b32_e32 v128, v6
	v_mov_b32_e32 v129, v6
	v_mov_b32_e32 v130, v6
	v_mov_b32_e32 v131, v6
	v_mov_b32_e32 v132, v6
	v_mov_b32_e32 v133, v6
	s_barrier
	s_branch .LBB0_270
	s_nop 0
	s_nop 0
	s_nop 0
	s_nop 0
	s_nop 0
	s_nop 0
	s_nop 0
	s_nop 0
	s_nop 0
	s_nop 0
	s_nop 0
	s_nop 0
	s_nop 0
	s_nop 0
	s_nop 0
	s_nop 0
	s_nop 0
	s_nop 0
	s_nop 0
	s_nop 0
	s_nop 0
	s_nop 0
	s_nop 0
	s_nop 0
	s_nop 0
	s_nop 0
	s_nop 0
	s_nop 0
	s_nop 0
	s_nop 0
	s_nop 0
	s_nop 0
	s_nop 0
	s_nop 0
	s_nop 0
	s_nop 0
	s_nop 0
	s_nop 0
	s_nop 0
	s_nop 0
	s_nop 0
	s_nop 0
	s_nop 0
	s_nop 0
	s_nop 0
	s_nop 0

; #define PG8_STAGE(bufoff, gbase, voff) do { _Pragma("unroll") for (int _i = 0; _i < 2; ++_i) \
;         __builtin_amdgcn_global_load_lds((const unsigned*)((const char*)(gbase) + (voff)[_i]), (LAS unsigned*)(lds + (bufoff) + ldsw + _i * 8192), 16, 0, 0); } while (0)
; #define PG8_WAIT_V(n) asm volatile("s_waitcnt vmcnt(" #n ")" ::: "memory")
; #define PG8_BAR __builtin_amdgcn_s_barrier()
;     __device__ __forceinline__ void operator()(const f32x4 (&acc)[2][2][4][2], const Unit& u, int wr, int wc, int fr, int fq) const {
;         const int row0 = u.pm * BM + wr * 64 + fr, j0 = 8 * fq, cbase = u.pn * BM + 64 * wc;
;         const f32x4 ba0 = *(const f32x4*)(bias + cbase + j0), ba1 = *(const f32x4*)(bias + cbase + j0 + 4), bb0 = *(const f32x4*)(bias + cbase + 32 + j0), bb1 = *(const f32x4*)(bias + cbase + 32 + j0 + 4);
;         const bool rot = u.pn < 9;
;         f32x4 TB[2][6];
; template <class Epi, class Sched>
; __device__ __forceinline__ void gemm_phase(LAS unsigned char* lds, const Gemm g, const Sched& S, const Epi& E) {
;     ...
;     PG8_WAIT_V(2); PG8_BAR;
;     PG8_STAGE(PG8_SB(1, 0), cB + kstep, voffB); PG8_STAGE(PG8_SA(1, 0), cA + kstep, voffA); PG8_STAGE(PG8_SB(1, 1), cB + hstepB + kstep, voffB);
;     PG8_WAIT_V(6); PG8_BAR;
.LBB0_507:
	v_lshrrev_b32_e32 v20, 1, v4
	v_and_b32_e32 v20, 24, v20
	v_and_b32_e32 v21, 15, v4
	v_lshlrev_b32_e32 v22, 1, v20
	v_lshlrev_b32_e32 v4, 2, v4
	s_and_b32 s20, s17, 3
	v_lshl_or_b32 v235, s18, 6, v21
	v_lshl_or_b32 v21, v21, 6, v22
	s_lshl_b32 s17, s18, 13
	v_and_b32_e32 v4, 32, v4
	s_add_i32 m0, s50, 0x18000
	v_lshl_add_u64 v[12:13], v[12:13], 0, s[36:37]
	v_bitop3_b32 v22, v21, s17, v4 bitop3:0xde
	s_lshl_b32 s17, s20, 12
	s_waitcnt vmcnt(2)
	s_barrier
	global_load_lds_dwordx4 v[12:13], off
	v_lshl_add_u64 v[10:11], v[10:11], 0, s[36:37]
	s_add_i32 m0, s50, 0x1a000
	s_add_i32 s54, s50, 0x8000
	s_add_i32 s55, s50, 0xa000
	global_load_lds_dwordx4 v[10:11], off
	v_lshl_add_u64 v[6:7], v[6:7], 0, s[36:37]
	s_mov_b32 m0, s54
	s_add_u32 s18, s42, 0x80080
	global_load_lds_dwordx4 v[6:7], off
	v_lshl_add_u64 v[6:7], v[8:9], 0, s[36:37]
	s_mov_b32 m0, s55
	s_addc_u32 s19, s43, 0
	global_load_lds_dwordx4 v[6:7], off
	s_add_i32 m0, s50, 0x1c000
	v_lshl_add_u64 v[6:7], s[18:19], 0, v[212:213]
	global_load_lds_dwordx4 v[6:7], off
	v_lshl_add_u64 v[6:7], s[18:19], 0, v[216:217]
	s_add_i32 m0, s50, 0x1e000
	v_bitop3_b32 v236, v21, s17, v4 bitop3:0xde
	global_load_lds_dwordx4 v[6:7], off
	v_lshlrev_b32_e32 v4, 2, v20
	v_lshl_add_u64 v[218:219], s[12:13], 0, v[4:5]
	v_lshl_add_u64 v[220:221], s[10:11], 0, v[4:5]
	v_lshl_add_u64 v[222:223], s[14:15], 0, v[4:5]
	v_lshlrev_b32_e32 v4, 15, v14
	v_and_b32_e32 v4, 0xffff0000, v4
	v_lshl_add_u32 v4, v15, 12, v4
	v_and_b32_e32 v6, 1, v14
	v_lshl_or_b32 v4, v6, 6, v4
	v_lshl_add_u32 v224, v16, 1, v4
	v_lshlrev_b32_e32 v4, 15, v17
	v_and_b32_e32 v4, 0xffff0000, v4
	s_waitcnt vmcnt(6)
	v_lshl_add_u32 v4, v18, 12, v4
	v_and_b32_e32 v6, 1, v17
	s_cmpk_lt_u32 s16, 0x100
	v_lshl_or_b32 v4, v6, 6, v4
	s_cselect_b64 s[16:17], -1, 0
	s_lshl_b32 s56, s20, 6
	v_mov_b32_e32 v225, v5
	v_lshl_add_u32 v226, v19, 1, v4
	v_mov_b32_e32 v227, v5
	s_mov_b32 s57, 0
	v_add_u32_e32 v237, 0, v22
	v_lshlrev_b32_e32 v4, 1, v20
	s_barrier
	s_branch .LBB0_510
	s_nop 0
	s_nop 0
	s_nop 0
	s_nop 0
	s_nop 0
	s_nop 0
	s_nop 0
	s_nop 0
	s_nop 0
	s_nop 0
	s_nop 0
	s_nop 0
	s_nop 0
	s_nop 0
	s_nop 0
	s_nop 0
	s_nop 0
	s_nop 0

; __device__ __forceinline__ float log2_gamma(int hd) { const float e = ldexpf(1.0f, -5 - hd); float p = 1.0f / 7.0f; p = p * e + 1.0f / 6.0f; p = p * e + 0.2f; p = p * e + 0.25f; p = p * e + 1.0f / 3.0f; p = p * e + 0.5f; p = p * e + 1.0f; return -1.44269504089f * e * p; }
; #define PG8_STAGE(bufoff, gbase, voff) do { _Pragma("unroll") for (int _i = 0; _i < 2; ++_i) \
;         __builtin_amdgcn_global_load_lds((const unsigned*)((const char*)(gbase) + (voff)[_i]), (LAS unsigned*)(lds + (bufoff) + ldsw + _i * 8192), 16, 0, 0); } while (0)
; #define PG8_WAIT_V(n) asm volatile("s_waitcnt vmcnt(" #n ")" ::: "memory")
; #define PG8_BAR __builtin_amdgcn_s_barrier()
;     __device__ __forceinline__ void operator()(const f32x4 (&acc)[2][2][4][2], const Unit& u, int wr, int wc, int fr, int fq) const {
;         const int row0 = u.pm * BM + wr * 64 + fr, j0 = wc * 32 + 8 * fq;
;         if (u.pn < 16) {
;             const int hd = u.pn & 7; const bool isq = u.pn < 8;
;             const float l2g = log2_gamma(hd);
;             f32x4 TB[2][6];
; template <class Epi, class Sched>
; __device__ __forceinline__ void gemm_phase(LAS unsigned char* lds, const Gemm g, const Sched& S, const Epi& E) {
;     ...
;     PG8_WAIT_V(2); PG8_BAR;
;     PG8_STAGE(PG8_SB(1, 0), cB + kstep, voffB); PG8_STAGE(PG8_SA(1, 0), cA + kstep, voffA); PG8_STAGE(PG8_SB(1, 1), cB + hstepB + kstep, voffB);
;     PG8_WAIT_V(6); PG8_BAR;
.LBB0_649:
	s_add_u32 s8, s14, 0xd000000
	v_lshrrev_b32_e32 v20, 1, v4
	s_addc_u32 s9, s15, 0
	v_and_b32_e32 v189, 15, v4
	v_and_b32_e32 v21, 24, v20
	s_add_u32 s10, s14, 0x100000
	v_lshlrev_b32_e32 v20, 1, v21
	v_lshlrev_b32_e32 v22, 6, v189
	v_lshlrev_b32_e32 v4, 2, v4
	s_addc_u32 s11, s15, 0
	s_and_b32 s18, s13, 3
	v_or_b32_e32 v23, v22, v20
	s_lshl_b32 s13, s16, 13
	v_and_b32_e32 v4, 32, v4
	s_add_i32 m0, s47, 0x18000
	v_lshl_add_u64 v[12:13], v[12:13], 0, s[36:37]
	s_lshl_b32 s51, s16, 6
	v_bitop3_b32 v24, v23, s13, v4 bitop3:0xde
	s_lshl_b32 s13, s18, 12
	s_waitcnt vmcnt(2)
	s_barrier
	global_load_lds_dwordx4 v[12:13], off
	v_lshl_add_u64 v[10:11], v[10:11], 0, s[36:37]
	s_add_i32 m0, s47, 0x1a000
	s_add_i32 s52, s47, 0x8000
	s_add_i32 s53, s47, 0xa000
	global_load_lds_dwordx4 v[10:11], off
	v_lshl_add_u64 v[6:7], v[6:7], 0, s[36:37]
	s_mov_b32 m0, s52
	s_add_u32 s16, s28, 0x80080
	global_load_lds_dwordx4 v[6:7], off
	v_lshl_add_u64 v[6:7], v[8:9], 0, s[36:37]
	s_mov_b32 m0, s53
	s_addc_u32 s17, s29, 0
	global_load_lds_dwordx4 v[6:7], off
	s_add_i32 m0, s47, 0x1c000
	v_lshl_add_u64 v[6:7], s[16:17], 0, v[182:183]
	global_load_lds_dwordx4 v[6:7], off
	v_lshl_add_u64 v[6:7], s[16:17], 0, v[186:187]
	s_add_i32 m0, s47, 0x1e000
	v_lshl_or_b32 v188, s18, 5, v21
	global_load_lds_dwordx4 v[6:7], off
	v_bitop3_b32 v231, v23, s13, v4 bitop3:0xde
	v_lshlrev_b32_e32 v4, 2, v188
	v_lshl_add_u64 v[6:7], s[14:15], 0, v[4:5]
	s_mov_b64 s[16:17], 0x200000
	s_cmpk_lt_u32 s12, 0x100
	v_lshl_add_u64 v[190:191], v[6:7], 0, s[16:17]
	s_mov_b64 s[16:17], 0x600000
	s_cselect_b64 s[12:13], -1, 0
	v_lshl_add_u64 v[192:193], v[6:7], 0, s[16:17]
	s_lshl_b32 s16, s18, 10
	s_add_u32 s14, s14, s16
	s_addc_u32 s15, s15, 0
	v_mov_b32_e32 v23, v5
	v_lshl_add_u64 v[6:7], s[14:15], 0, v[22:23]
	v_mov_b32_e32 v21, v5
	v_lshlrev_b32_e32 v4, 15, v14
	v_lshl_add_u64 v[6:7], v[6:7], 0, v[20:21]
	s_mov_b64 s[14:15], 0x5000000
	v_and_b32_e32 v4, 0xffff0000, v4
	v_lshl_add_u64 v[194:195], v[6:7], 0, s[14:15]
	v_lshl_add_u32 v4, v15, 12, v4
	v_and_b32_e32 v6, 1, v14
	v_lshl_or_b32 v4, v6, 6, v4
	v_lshl_add_u32 v196, v16, 1, v4
	v_lshlrev_b32_e32 v4, 15, v17
	v_and_b32_e32 v4, 0xffff0000, v4
	s_waitcnt vmcnt(6)
	v_lshl_add_u32 v4, v18, 12, v4
	v_and_b32_e32 v6, 1, v17
	v_lshl_or_b32 v4, v6, 6, v4
	v_mov_b32_e32 v197, v5
	v_lshl_add_u32 v212, v19, 1, v4
	v_mov_b32_e32 v213, v5
	s_mov_b32 s54, 0
	v_add_u32_e32 v235, 0, v24
	s_barrier
	s_branch .LBB0_652
	s_nop 0
	s_nop 0
	s_nop 0
	s_nop 0
	s_nop 0
	s_nop 0
	s_nop 0
	s_nop 0
	s_nop 0
	s_nop 0
	s_nop 0
	s_nop 0
	s_nop 0
	s_nop 0
	s_nop 0
	s_nop 0

; #define PG8_STAGE(bufoff, gbase, voff) do { _Pragma("unroll") for (int _i = 0; _i < 2; ++_i) \
;         __builtin_amdgcn_global_load_lds((const unsigned*)((const char*)(gbase) + (voff)[_i]), (LAS unsigned*)(lds + (bufoff) + ldsw + _i * 8192), 16, 0, 0); } while (0)
; #define PG8_WAIT_V(n) asm volatile("s_waitcnt vmcnt(" #n ")" ::: "memory")
; #define PG8_BAR __builtin_amdgcn_s_barrier()
; template <class Epi, class Sched>
; __device__ __forceinline__ void gemm_phase(LAS unsigned char* lds, const Gemm g, const Sched& S, const Epi& E) {
;     ...
;     f32x4 acc[2][2][4][2];
; #pragma unroll
;     for (int a = 0; a < 2; ++a)
; #pragma unroll
;         for (int b = 0; b < 2; ++b)
; #pragma unroll
;             for (int m = 0; m < 4; ++m)
; #pragma unroll
;                 for (int n = 0; n < 2; ++n) acc[a][b][m][n] = (f32x4){0.f, 0.f, 0.f, 0.f};
;     ...
;     PG8_STAGE(PG8_SB(0, 0), cB, voffB); PG8_STAGE(PG8_SB(0, 1), cB + hstepB, voffB); PG8_STAGE(PG8_SA(0, 0), cA, voffA); PG8_STAGE(PG8_SA(0, 1), cA + hstepA, voffA);
;     if (wr == 1) PG8_BAR;
;     PG8_WAIT_V(2); PG8_BAR;
;     PG8_STAGE(PG8_SB(1, 0), cB + kstep, voffB); PG8_STAGE(PG8_SA(1, 0), cA + kstep, voffA); PG8_STAGE(PG8_SB(1, 1), cB + hstepB + kstep, voffB);
;     PG8_WAIT_V(6); PG8_BAR;
;     for (;;) {
.LBB0_995:
	v_mov_b32_e32 v139, v5
	v_lshl_add_u64 v[10:11], s[24:25], 0, v[138:139]
	v_mov_b32_e32 v135, v5
	v_lshl_add_u64 v[12:13], s[24:25], 0, v[134:135]
	v_mov_b32_e32 v141, v5
	s_add_i32 m0, s58, 0x18000
	v_lshl_add_u64 v[10:11], v[10:11], 0, s[36:37]
	v_lshl_add_u64 v[18:19], s[26:27], 0, v[140:141]
	v_mov_b32_e32 v137, v5
	s_waitcnt vmcnt(2)
	s_barrier
	global_load_lds_dwordx4 v[10:11], off
	v_lshl_add_u64 v[10:11], v[12:13], 0, s[36:37]
	s_add_i32 m0, s58, 0x1a000
	s_add_i32 s62, s58, 0x8000
	v_lshl_add_u64 v[20:21], s[26:27], 0, v[136:137]
	global_load_lds_dwordx4 v[10:11], off
	v_lshl_add_u64 v[10:11], v[18:19], 0, s[36:37]
	s_mov_b32 m0, s62
	s_add_i32 s63, s58, 0xa000
	v_lshl_add_u64 v[14:15], s[4:5], 0, v[138:139]
	global_load_lds_dwordx4 v[10:11], off
	v_lshl_add_u64 v[10:11], v[20:21], 0, s[36:37]
	s_mov_b32 m0, s63
	v_lshl_add_u64 v[16:17], s[4:5], 0, v[134:135]
	global_load_lds_dwordx4 v[10:11], off
	s_add_i32 m0, s58, 0x1c000
	v_lshl_add_u64 v[10:11], v[14:15], 0, s[36:37]
	global_load_lds_dwordx4 v[10:11], off
	v_lshl_add_u64 v[10:11], v[16:17], 0, s[36:37]
	s_add_i32 m0, s58, 0x1e000
	v_and_b32_e32 v168, 15, v169
	global_load_lds_dwordx4 v[10:11], off
	v_and_b32_e32 v9, 48, v169
	v_lshlrev_b32_e32 v10, 2, v169
	s_and_b32 s54, s50, 3
	s_lshr_b32 s64, s6, 6
	v_lshl_or_b32 v9, v168, 6, v9
	s_lshl_b32 s4, s52, 13
	v_and_b32_e32 v10, 32, v10
	v_bitop3_b32 v11, v9, s4, v10 bitop3:0xde
	s_lshl_b32 s4, s54, 12
	s_add_i32 s65, s64, -2
	s_cmpk_lt_u32 s51, 0x100
	v_bitop3_b32 v148, v9, s4, v10 bitop3:0xde
	s_cselect_b64 s[28:29], -1, 0
	s_add_u32 s4, s34, 0x80
	v_add_u32_e32 v4, v8, v4
	s_addc_u32 s5, 0, 0
	v_add_lshl_u32 v4, v4, v7, 1
	v_add_u32_e32 v2, v6, v2
	v_lshl_add_u64 v[142:143], s[4:5], 0, v[4:5]
	v_add_lshl_u32 v4, v2, v3, 1
	s_waitcnt vmcnt(6)
	v_lshl_add_u64 v[144:145], s[4:5], 0, v[4:5]
	v_mov_b32_e32 v4, v5
	v_mov_b32_e32 v2, v5
	v_mov_b32_e32 v3, v5
	v_add_u32_e32 v149, 0, v11
	v_mov_b64_e32 v[8:9], v[4:5]
	v_mov_b64_e32 v[12:13], v[4:5]
	v_mov_b64_e32 v[16:17], v[4:5]
	v_mov_b64_e32 v[20:21], v[4:5]
	v_mov_b64_e32 v[24:25], v[4:5]
	v_mov_b64_e32 v[32:33], v[4:5]
	v_mov_b64_e32 v[40:41], v[4:5]
	v_mov_b64_e32 v[48:49], v[4:5]
	v_mov_b64_e32 v[28:29], v[4:5]
	v_mov_b64_e32 v[36:37], v[4:5]
	v_mov_b64_e32 v[44:45], v[4:5]
	v_mov_b64_e32 v[52:53], v[4:5]
	v_mov_b64_e32 v[56:57], v[4:5]
	v_mov_b64_e32 v[60:61], v[4:5]
	v_mov_b64_e32 v[64:65], v[4:5]
	v_mov_b64_e32 v[68:69], v[4:5]
	v_mov_b64_e32 v[72:73], v[4:5]
	v_mov_b64_e32 v[76:77], v[4:5]
	v_mov_b64_e32 v[80:81], v[4:5]
	v_mov_b64_e32 v[84:85], v[4:5]
	v_mov_b64_e32 v[88:89], v[4:5]
	v_mov_b64_e32 v[96:97], v[4:5]
	v_mov_b64_e32 v[104:105], v[4:5]
	v_mov_b64_e32 v[116:117], v[4:5]
	v_mov_b64_e32 v[92:93], v[4:5]
	v_mov_b64_e32 v[100:101], v[4:5]
	v_mov_b64_e32 v[108:109], v[4:5]
	v_mov_b64_e32 v[112:113], v[4:5]
	v_mov_b64_e32 v[120:121], v[4:5]
	v_mov_b64_e32 v[124:125], v[4:5]
	v_mov_b64_e32 v[128:129], v[4:5]
	v_mov_b64_e32 v[132:133], v[4:5]
	v_readlane_b32 s4, v254, 13
	s_mov_b32 s66, 0
	v_mov_b64_e32 v[6:7], v[2:3]
	v_mov_b64_e32 v[10:11], v[2:3]
	v_mov_b64_e32 v[14:15], v[2:3]
	v_mov_b64_e32 v[18:19], v[2:3]
	v_mov_b64_e32 v[22:23], v[2:3]
	v_mov_b64_e32 v[30:31], v[2:3]
	v_mov_b64_e32 v[38:39], v[2:3]
	v_mov_b64_e32 v[46:47], v[2:3]
	v_mov_b64_e32 v[26:27], v[2:3]
	v_mov_b64_e32 v[34:35], v[2:3]
	v_mov_b64_e32 v[42:43], v[2:3]
	v_mov_b64_e32 v[50:51], v[2:3]
	v_mov_b64_e32 v[54:55], v[2:3]
	v_mov_b64_e32 v[58:59], v[2:3]
	v_mov_b64_e32 v[62:63], v[2:3]
	v_mov_b64_e32 v[66:67], v[2:3]
	v_mov_b64_e32 v[70:71], v[2:3]
	v_mov_b64_e32 v[74:75], v[2:3]
	v_mov_b64_e32 v[78:79], v[2:3]
	v_mov_b64_e32 v[82:83], v[2:3]
	v_mov_b64_e32 v[86:87], v[2:3]
	v_mov_b64_e32 v[94:95], v[2:3]
	v_mov_b64_e32 v[102:103], v[2:3]
	v_mov_b64_e32 v[114:115], v[2:3]
	v_mov_b64_e32 v[90:91], v[2:3]
	v_mov_b64_e32 v[98:99], v[2:3]
	v_mov_b64_e32 v[106:107], v[2:3]
	v_mov_b64_e32 v[110:111], v[2:3]
	v_mov_b64_e32 v[118:119], v[2:3]
	v_mov_b64_e32 v[122:123], v[2:3]
	v_mov_b64_e32 v[126:127], v[2:3]
	v_mov_b64_e32 v[130:131], v[2:3]
	s_mov_b32 s6, s4
	v_readlane_b32 s53, v253, 61
	s_barrier
	s_branch .LBB0_998
	s_nop 0
	s_nop 0
	s_nop 0
	s_nop 0
	s_nop 0
	s_nop 0
	s_nop 0
	s_nop 0
	s_nop 0
	s_nop 0
	s_nop 0
	s_nop 0
	s_nop 0
	s_nop 0
	s_nop 0
	s_nop 0
